# phase A: odd workgroups run the sample unit before the states unit (bandwidth-heavy and latency-heavy units overlap across the grid)
# baseline (speedup 1.0000x reference)
.LBB0_673:
	s_and_b64 vcc, exec, s[2:3]
	s_cbranch_vccz .LBB0_783
	v_readlane_b32 s2, v254, 31
	s_cmpk_gt_i32 s2, 0x1ff
	s_cbranch_scc1 .LBB0_783
	v_writelane_b32 v255, s90, 28
	v_readlane_b32 s93, v254, 31
	v_readlane_b32 s100, v254, 32
	s_cmpk_lg_i32 s100, 0x100
	s_cbranch_scc1 .Lpa_noswap
	s_bitcmp1_b32 s93, 0
	s_cselect_b32 s101, s100, 0
	s_cselect_b32 s100, 0xffffff00, s100
	s_add_i32 s93, s93, s101
.Lpa_noswap:
	v_readlane_b32 s12, v254, 53
	v_writelane_b32 v255, s91, 29
	v_readlane_b32 s14, v254, 55
	v_readlane_b32 s8, v255, 2
	s_lshl_b32 s10, s8, 4
	s_mul_i32 s3, s8, 0x6000
	s_lshl_b32 s28, s8, 7
	s_ashr_i32 s11, s10, 31
	s_mul_hi_i32 s2, s8, 0x6000
	s_waitcnt lgkmcnt(0)
	s_add_u32 s90, s78, s3
	s_mul_i32 s5, s8, 0x1800
	s_addc_u32 s91, s79, s2
	s_mul_hi_i32 s4, s8, 0x1800
	s_add_u32 s78, s80, s5
	s_mul_i32 s7, s8, 0x688000
	s_addc_u32 s79, s81, s4
	v_readlane_b32 s4, v255, 17
	s_mul_hi_i32 s6, s8, 0x688000
	v_readlane_b32 s5, v255, 18
	s_add_u32 s29, s4, s7
	s_addc_u32 s6, s5, s6
	s_lshl_b64 s[2:3], s[10:11], 2
	s_add_u32 s60, s84, s2
	s_addc_u32 s61, s85, s3
	s_add_u32 s62, s90, 0x1800
	s_addc_u32 s63, s91, 0
	s_add_u32 s72, s90, 0x3000
	s_addc_u32 s73, s91, 0
	s_add_u32 s74, s90, 0x4800
	s_addc_u32 s75, s91, 0
	s_bitcmp1_b32 s93, 0
	v_readlane_b32 s2, v254, 32
	s_cselect_b64 s[76:77], -1, 0
	s_bitcmp1_b32 s2, 0
	s_cselect_b64 s[80:81], -1, 0
	v_readlane_b32 s15, v254, 56
	s_add_u32 s2, s14, 0xaba4020
	v_readlane_b32 s13, v254, 54
	s_addc_u32 s3, s15, 0
	v_writelane_b32 v255, s2, 33
	v_readlane_b32 s12, v254, 33
	s_add_i32 s11, s93, 0xffffff00
	v_writelane_b32 v255, s3, 34
	s_lshl_b32 s2, s8, 11
	v_readlane_b32 s22, v254, 43
	v_readlane_b32 s23, v254, 44
	s_add_u32 s84, s22, 0x18020
	v_readlane_b32 s26, v254, 47
	s_addc_u32 s85, s23, 0
	v_readlane_b32 s27, v254, 48
	s_add_u32 s26, s4, 0x7918a00
	s_addc_u32 s27, s5, 0
	s_add_u32 s4, s29, 0x680200
	v_writelane_b32 v255, s2, 26
	s_mov_b32 s67, s6
	s_addc_u32 s5, s6, 0
	s_mov_b32 s92, s93
	v_mov_b32_e32 v157, v207
	v_readlane_b32 s13, v254, 34
	v_readlane_b32 s14, v254, 35
	v_readlane_b32 s15, v254, 36
	v_readlane_b32 s16, v254, 37
	v_readlane_b32 s17, v254, 38
	v_readlane_b32 s18, v254, 39
	v_readlane_b32 s19, v254, 40
	v_readlane_b32 s20, v254, 41
	v_readlane_b32 s21, v254, 42
	v_readlane_b32 s24, v254, 45
	v_readlane_b32 s25, v254, 46
	s_branch .LBB0_677

.LBB0_676:
	s_mov_b32 s2, s100
	s_add_i32 s93, s93, s2
	s_xor_b64 s[76:77], s[76:77], s[80:81]
	s_add_i32 s11, s11, s2
	s_add_i32 s92, s92, s2
	s_cmpk_gt_i32 s93, 0x1ff
	s_cbranch_scc1 .LBB0_782
	s_cmp_lt_i32 s93, 0
	s_cbranch_scc1 .LBB0_782
